# merge: gate staging overlapped (first-segment gates read inside the K loop, next gate tile issued behind a slab, counted wait on the prestaged slab)
# baseline (speedup 1.0000x reference)
.LBB0_112:
	s_lshl_b32 s2, s10, 10
	s_lshl_b32 s16, s10, 9
	s_add_i32 s12, s2, 0x400
	s_cmp_lg_u32 s10, 2
	s_cselect_b64 s[2:3], -1, 0
	s_and_b64 s[4:5], s[2:3], exec
	s_cselect_b32 s4, s12, 0x800
	s_lshl_b32 s12, s10, 11
	v_lshl_add_u64 v[4:5], v[84:85], 0, s[12:13]
	s_lshl_b32 s4, s4, 1
	s_mov_b32 s5, s13
	v_lshl_add_u64 v[6:7], v[84:85], 0, s[4:5]
	s_cmp_eq_u32 s10, 0
	s_cbranch_scc0 .Lmg_reuse
	s_add_u32 m0, s36, 0x10000
	s_add_u32 s34, s30, 0x0
	s_addc_u32 s35, s31, 0
	global_load_lds_dwordx4 v170, s[34:35]
	s_add_u32 m0, s36, 0x11000
	s_add_u32 s34, s30, 0x37000
	s_addc_u32 s35, s31, 0
	global_load_lds_dwordx4 v170, s[34:35]
	s_add_u32 m0, s36, 0x12000
	s_add_u32 s34, s30, 0x6e000
	s_addc_u32 s35, s31, 0
	global_load_lds_dwordx4 v170, s[34:35]
	s_add_u32 m0, s36, 0x3000
	s_add_u32 s34, s30, 0xa5000
	s_addc_u32 s35, s31, 0
	global_load_lds_dwordx4 v170, s[34:35]
	s_add_u32 m0, s36, 0xb000
	s_add_u32 s34, s30, 0xdc000
	s_addc_u32 s35, s31, 0
	global_load_lds_dwordx4 v170, s[34:35]
	s_add_u32 m0, s36, 0x13000
	s_add_u32 s34, s30, 0x113000
	s_addc_u32 s35, s31, 0
	global_load_lds_dwordx4 v170, s[34:35]
	s_branch .Lmg_ld_done

.LBB0_115:
	v_lshl_add_u64 v[174:175], v[90:91], 0, s[4:5]
	s_mov_b64 s[18:19], 0x10280080
	v_lshl_add_u64 v[176:177], v[174:175], 0, s[18:19]
	s_and_b32 s18, s17, 0x2000
	v_lshl_add_u32 v69, s18, 2, v145
	v_add_u32_e32 v71, 0x1000, v69
	v_readfirstlane_b32 s18, v69
	s_mov_b32 m0, s18
	s_mov_b64 s[18:19], 0x10298080
	s_cmp_eq_u32 s10, 1
	s_cbranch_scc0 .Lmg_w0
	s_cmp_eq_u32 s4, 0
	s_cbranch_scc0 .Lmg_w0
	s_waitcnt vmcnt(6)
	s_branch .Lmg_w1

.Lmg_w1:
	s_barrier
	global_load_lds_dwordx4 v[176:177], off
	v_lshl_add_u64 v[176:177], v[174:175], 0, s[18:19]
	v_readfirstlane_b32 s18, v71
	s_mov_b32 m0, s18
	s_mov_b64 s[18:19], 0x102b0080
	v_add_u32_e32 v71, 0x2000, v69
	v_lshl_add_u64 v[174:175], v[174:175], 0, s[18:19]
	v_readfirstlane_b32 s18, v71
	global_load_lds_dwordx4 v[176:177], off
	s_mov_b32 m0, s18
	s_mov_b64 s[18:19], 0x3800080
	global_load_lds_dwordx4 v[174:175], off
	v_lshl_add_u64 v[174:175], v[92:93], 0, s[4:5]
	v_add_u32_e32 v71, 0x4000, v69
	v_lshl_add_u64 v[176:177], v[174:175], 0, s[18:19]
	v_readfirstlane_b32 s18, v71
	s_mov_b32 m0, s18
	s_mov_b64 s[18:19], 0x3808080
	v_add_u32_e32 v71, 0x5000, v69
	global_load_lds_dwordx4 v[176:177], off
	v_lshl_add_u64 v[176:177], v[174:175], 0, s[18:19]
	v_readfirstlane_b32 s18, v71
	s_mov_b32 m0, s18
	s_mov_b64 s[18:19], 0x3810080
	v_add_u32_e32 v71, 0x6000, v69
	global_load_lds_dwordx4 v[176:177], off
	v_lshl_add_u64 v[176:177], v[174:175], 0, s[18:19]
	v_readfirstlane_b32 s18, v71
	s_mov_b32 m0, s18
	s_mov_b64 s[18:19], 0x3818080
	v_add_u32_e32 v69, 0x7000, v69
	v_lshl_add_u64 v[174:175], v[174:175], 0, s[18:19]
	v_readfirstlane_b32 s18, v69
	global_load_lds_dwordx4 v[176:177], off
	s_mov_b32 m0, s18
	s_lshl_b32 s18, s12, 1
	global_load_lds_dwordx4 v[174:175], off
	s_cmp_eq_u32 s10, 0
	s_cbranch_scc0 .Lmg_d1
	s_cmpk_eq_u32 s4, 0x80
	s_cbranch_scc0 .Lmg_d1
	s_add_u32 m0, s36, 0x10000
	s_add_u32 s34, s30, 0x800
	s_addc_u32 s35, s31, 0
	global_load_lds_dwordx4 v170, s[34:35]
	s_add_u32 m0, s36, 0x11000
	s_add_u32 s34, s30, 0x37800
	s_addc_u32 s35, s31, 0
	global_load_lds_dwordx4 v170, s[34:35]
	s_add_u32 m0, s36, 0x12000
	s_add_u32 s34, s30, 0x6e800
	s_addc_u32 s35, s31, 0
	global_load_lds_dwordx4 v170, s[34:35]
	s_add_u32 m0, s36, 0x3000
	s_add_u32 s34, s30, 0xa5800
	s_addc_u32 s35, s31, 0
	global_load_lds_dwordx4 v170, s[34:35]
	s_add_u32 m0, s36, 0xb000
	s_add_u32 s34, s30, 0xdc800
	s_addc_u32 s35, s31, 0
	global_load_lds_dwordx4 v170, s[34:35]
	s_add_u32 m0, s36, 0x13000
	s_add_u32 s34, s30, 0x113800
	s_addc_u32 s35, s31, 0
	global_load_lds_dwordx4 v170, s[34:35]
.Lmg_d1:
	s_and_b32 s18, s18, 0x8000
	v_lshl_add_u32 v69, v146, 1, s18
	ds_read_b128 v[174:177], v69
	ds_read_b128 v[178:181], v69 offset:2048
	ds_read_b128 v[212:215], v69 offset:4096
	v_lshl_or_b32 v69, v147, 1, s18
	ds_read_b128 v[216:219], v69 offset:16384
	ds_read_b128 v[220:223], v69 offset:18432
	ds_read_b128 v[234:237], v69 offset:20480
	ds_read_b128 v[238:241], v69 offset:22528
	v_lshl_add_u32 v69, v148, 1, s18
	s_waitcnt lgkmcnt(0)
	v_mfma_f32_16x16x32_bf16 v[48:51], v[216:219], v[174:177], v[48:51]
	s_add_u32 s4, s4, 0x80
	s_addc_u32 s5, s5, 0
	s_addk_i32 s12, 0x4000
	v_mfma_f32_16x16x32_bf16 v[8:11], v[220:223], v[174:177], v[8:11]
	s_addk_i32 s17, 0x2000
	s_cmpk_eq_i32 s4, 0x380
	v_mfma_f32_16x16x32_bf16 v[12:15], v[234:237], v[174:177], v[12:15]
	v_mfma_f32_16x16x32_bf16 v[16:19], v[238:241], v[174:177], v[16:19]
	v_mfma_f32_16x16x32_bf16 v[20:23], v[216:219], v[178:181], v[20:23]
	v_mfma_f32_16x16x32_bf16 v[24:27], v[220:223], v[178:181], v[24:27]
	v_mfma_f32_16x16x32_bf16 v[28:31], v[234:237], v[178:181], v[28:31]
	v_mfma_f32_16x16x32_bf16 v[32:35], v[238:241], v[178:181], v[32:35]
	v_mfma_f32_16x16x32_bf16 v[36:39], v[216:219], v[212:215], v[36:39]
	v_mfma_f32_16x16x32_bf16 v[40:43], v[220:223], v[212:215], v[40:43]
	v_mfma_f32_16x16x32_bf16 v[44:47], v[234:237], v[212:215], v[44:47]
	v_mfma_f32_16x16x32_bf16 v[0:3], v[238:241], v[212:215], v[0:3]
	ds_read_b128 v[174:177], v69
	ds_read_b128 v[178:181], v69 offset:2048
	ds_read_b128 v[212:215], v69 offset:4096
	v_lshl_or_b32 v69, v149, 1, s18
	ds_read_b128 v[216:219], v69 offset:16384
	ds_read_b128 v[220:223], v69 offset:18432
	ds_read_b128 v[234:237], v69 offset:20480
	ds_read_b128 v[238:241], v69 offset:22528
	s_waitcnt lgkmcnt(0)
	v_mfma_f32_16x16x32_bf16 v[48:51], v[216:219], v[174:177], v[48:51]
	v_mfma_f32_16x16x32_bf16 v[8:11], v[220:223], v[174:177], v[8:11]
	v_mfma_f32_16x16x32_bf16 v[12:15], v[234:237], v[174:177], v[12:15]
	v_mfma_f32_16x16x32_bf16 v[16:19], v[238:241], v[174:177], v[16:19]
	v_mfma_f32_16x16x32_bf16 v[20:23], v[216:219], v[178:181], v[20:23]
	v_mfma_f32_16x16x32_bf16 v[24:27], v[220:223], v[178:181], v[24:27]
	v_mfma_f32_16x16x32_bf16 v[28:31], v[234:237], v[178:181], v[28:31]
	v_mfma_f32_16x16x32_bf16 v[32:35], v[238:241], v[178:181], v[32:35]
	v_mfma_f32_16x16x32_bf16 v[36:39], v[216:219], v[212:215], v[36:39]
	v_mfma_f32_16x16x32_bf16 v[40:43], v[220:223], v[212:215], v[40:43]
	v_mfma_f32_16x16x32_bf16 v[44:47], v[234:237], v[212:215], v[44:47]
	v_mfma_f32_16x16x32_bf16 v[0:3], v[238:241], v[212:215], v[0:3]
	s_cmp_eq_u32 s10, 0
	s_cbranch_scc0 .Lmg_g1
	s_cmpk_eq_u32 s4, 0x80
	s_cbranch_scc0 .Lmg_g1
	v_add_u32_e32 v94, v224, v244
	v_add_u32_e32 v95, v225, v245
	v_add_u32_e32 v98, v242, v246
	v_add_u32_e32 v99, v243, v172
	v_lshrrev_b32_e32 v94, 1, v94
	v_lshrrev_b32_e32 v95, 1, v95
	v_lshrrev_b32_e32 v98, 1, v98
	v_lshrrev_b32_e32 v99, 1, v99
	ds_read_b64 v[140:141], v224
	ds_read_b64 v[106:107], v225
	ds_read_b64 v[114:115], v242
	ds_read_b64 v[122:123], v243
	ds_read_b64 v[116:117], v244
	ds_read_b64 v[108:109], v245
	ds_read_b64 v[100:101], v246
	ds_read_b64 v[96:97], v172
	ds_read_b64 v[130:131], v94
	ds_read_b64 v[138:139], v95
	ds_read_b64 v[132:133], v98
	ds_read_b64 v[124:125], v99
	s_waitcnt lgkmcnt(0)
.Lmg_g1:
	s_cmpk_eq_i32 s4, 0x380
	s_cbranch_scc0 .LBB0_115
	s_waitcnt vmcnt(0)
	s_or_b64 s[56:57], s[48:49], s[2:3]
	s_andn2_b64 vcc, exec, s[56:57]
	s_barrier
	s_cbranch_vccnz .LBB0_118
	s_lshl_b32 s4, s16, 1
	s_add_u32 s4, s1, s4
	s_addc_u32 s5, s11, 0
	s_add_u32 s12, s4, 0x400
	s_addc_u32 s18, s5, 0
	s_add_i32 s16, s8, s10
	s_and_b64 s[4:5], s[2:3], exec
	s_cselect_b32 s4, s16, s46
	s_ashr_i32 s5, s4, 31
	s_lshl_b64 s[4:5], s[4:5], 20
	s_and_b64 s[16:17], s[2:3], exec
	v_readlane_b32 s20, v249, 41
	s_cselect_b32 s16, s53, s55
	s_cselect_b32 s17, s52, s54
	v_readlane_b32 s21, v249, 42
	s_add_u32 s4, s20, s4
	s_addc_u32 s5, s21, s5
	s_add_u32 s17, s4, s17
	s_addc_u32 s16, s5, s16
	s_and_b64 s[4:5], s[2:3], exec
	s_cselect_b32 s4, s18, s14
	s_cselect_b32 s5, s12, s15
	v_mov_b32_e32 v174, s5
	v_mov_b32_e32 v175, s4
	s_and_b64 s[4:5], s[56:57], exec
	s_cselect_b32 s4, s16, 0
	s_cselect_b32 s5, s17, 0
	v_mov_b32_e32 v176, s5
	v_mov_b32_e32 v177, s4
	v_lshl_add_u64 v[174:175], v[52:53], 1, v[174:175]
	v_lshl_add_u64 v[174:175], v[174:175], 0, v[152:153]
	v_lshl_add_u64 v[176:177], v[56:57], 1, v[176:177]
	s_mov_b64 s[4:5], 0x30000
	v_lshl_add_u64 v[176:177], v[176:177], 0, v[152:153]
	v_lshl_add_u64 v[180:181], v[174:175], 0, s[4:5]
	s_mov_b64 s[4:5], 0x8000
	v_lshl_add_u64 v[182:183], v[176:177], 0, s[4:5]
	s_mov_b64 s[4:5], 0x10000
	v_lshl_add_u64 v[212:213], v[176:177], 0, s[4:5]
	v_readfirstlane_b32 s4, v145
	s_mov_b64 s[16:17], 0x18000
	s_mov_b32 m0, s4
	v_readfirstlane_b32 s4, v67
	v_lshl_add_u64 v[178:179], v[174:175], 0, s[16:17]
	global_load_lds_dwordx4 v[174:175], off
	s_mov_b32 m0, s4
	v_readfirstlane_b32 s4, v65
	global_load_lds_dwordx4 v[178:179], off
	s_mov_b32 m0, s4
	v_readfirstlane_b32 s4, v7
	global_load_lds_dwordx4 v[180:181], off
	s_mov_b32 m0, s4
	v_readfirstlane_b32 s4, v6
	global_load_lds_dwordx4 v[176:177], off
	s_mov_b32 m0, s4
	v_readfirstlane_b32 s4, v5
	global_load_lds_dwordx4 v[182:183], off
	s_mov_b32 m0, s4
	v_readfirstlane_b32 s4, v4
	v_lshl_add_u64 v[214:215], v[176:177], 0, s[16:17]
	global_load_lds_dwordx4 v[212:213], off
	s_mov_b32 m0, s4
	s_nop 0
	global_load_lds_dwordx4 v[214:215], off
